# instruction selection: GEMM tile headers zero the 128 accumulators with 64 v_mov_b64 instead of 128 v_mov_b32 (main G1 and G2)
# speedup vs baseline: 1.0117x; 1.0117x over previous
.LBB0_56:
	s_ashr_i32 s95, s94, 31
	s_lshl_b64 s[6:7], s[94:95], 19
	v_readlane_b32 s9, v253, 5
	s_add_u32 s80, s9, s6
	v_readlane_b32 s6, v253, 6
	s_addc_u32 s81, s6, s7
	s_and_b64 s[6:7], s[42:43], exec
	s_cselect_b32 s9, s81, s1
	s_cselect_b32 s11, s80, s0
	s_ashr_i32 s93, s92, 31
	s_lshl_b64 s[6:7], s[92:93], 19
	v_readlane_b32 s12, v253, 61
	s_add_u32 s82, s12, s6
	v_readlane_b32 s6, v253, 62
	s_addc_u32 s83, s6, s7
	s_and_b64 s[6:7], s[42:43], exec
	s_cselect_b32 s12, s83, s5
	s_cselect_b32 s13, s82, s4
	s_add_u32 s0, s0, 0x40080
	s_addc_u32 s1, s1, 0
	s_add_u32 s14, s4, 0x100
	v_mov_b64_e32 v[2:3], 0
	v_mov_b64_e32 v[4:5], 0
	v_mov_b64_e32 v[6:7], 0
	v_mov_b64_e32 v[8:9], 0
	v_mov_b64_e32 v[10:11], 0
	v_mov_b64_e32 v[12:13], 0
	v_mov_b64_e32 v[14:15], 0
	v_mov_b64_e32 v[16:17], 0
	v_mov_b64_e32 v[26:27], 0
	v_mov_b64_e32 v[28:29], 0
	v_mov_b64_e32 v[30:31], 0
	v_mov_b64_e32 v[32:33], 0
	v_mov_b64_e32 v[42:43], 0
	v_mov_b64_e32 v[44:45], 0
	v_mov_b64_e32 v[46:47], 0
	v_mov_b64_e32 v[48:49], 0
	v_mov_b64_e32 v[50:51], 0
	v_mov_b64_e32 v[52:53], 0
	v_mov_b64_e32 v[54:55], 0
	v_mov_b64_e32 v[56:57], 0
	v_mov_b64_e32 v[58:59], 0
	v_mov_b64_e32 v[60:61], 0
	v_mov_b64_e32 v[62:63], 0
	v_mov_b64_e32 v[64:65], 0
	v_mov_b64_e32 v[66:67], 0
	v_mov_b64_e32 v[68:69], 0
	v_mov_b64_e32 v[70:71], 0
	v_mov_b64_e32 v[72:73], 0
	v_mov_b64_e32 v[74:75], 0
	v_mov_b64_e32 v[76:77], 0
	v_mov_b64_e32 v[78:79], 0
	v_mov_b64_e32 v[80:81], 0
	v_mov_b64_e32 v[82:83], 0
	v_mov_b64_e32 v[84:85], 0
	v_mov_b64_e32 v[86:87], 0
	v_mov_b64_e32 v[88:89], 0
	v_mov_b64_e32 v[90:91], 0
	v_mov_b64_e32 v[92:93], 0
	v_mov_b64_e32 v[94:95], 0
	v_mov_b64_e32 v[96:97], 0
	v_mov_b64_e32 v[98:99], 0
	v_mov_b64_e32 v[100:101], 0
	v_mov_b64_e32 v[102:103], 0
	v_mov_b64_e32 v[104:105], 0
	v_mov_b64_e32 v[106:107], 0
	v_mov_b64_e32 v[108:109], 0
	v_mov_b64_e32 v[110:111], 0
	v_mov_b64_e32 v[112:113], 0
	v_mov_b64_e32 v[114:115], 0
	v_mov_b64_e32 v[116:117], 0
	v_mov_b64_e32 v[118:119], 0
	v_mov_b64_e32 v[120:121], 0
	v_mov_b64_e32 v[122:123], 0
	v_mov_b64_e32 v[124:125], 0
	v_mov_b64_e32 v[126:127], 0
	v_mov_b64_e32 v[128:129], 0
	v_mov_b64_e32 v[130:131], 0
	v_mov_b64_e32 v[132:133], 0
	v_mov_b64_e32 v[134:135], 0
	v_mov_b64_e32 v[136:137], 0
	v_mov_b64_e32 v[138:139], 0
	v_mov_b64_e32 v[140:141], 0
	v_mov_b64_e32 v[142:143], 0
	v_mov_b64_e32 v[144:145], 0
	s_addc_u32 s15, s5, 0
	s_mov_b32 s16, -2

.LBB0_1369:
	s_ashr_i32 s9, s8, 31
	s_lshl_b64 s[10:11], s[8:9], 19
	v_readlane_b32 s7, v253, 15
	s_add_u32 s10, s7, s10
	v_readlane_b32 s7, v253, 16
	s_addc_u32 s11, s7, s11
	s_and_b64 s[12:13], s[38:39], exec
	s_cselect_b32 s9, s11, s15
	s_cselect_b32 s69, s10, s14
	s_ashr_i32 s7, s6, 31
	s_lshl_b64 s[12:13], s[6:7], 19
	s_add_u32 s12, s40, s12
	s_addc_u32 s13, s41, s13
	s_and_b64 s[18:19], s[38:39], exec
	s_cselect_b32 s7, s13, s17
	s_cselect_b32 s70, s12, s16
	s_add_u32 s14, s14, 0x40080
	s_addc_u32 s15, s15, 0
	s_add_u32 s71, s16, 0x100
	v_mov_b64_e32 v[2:3], 0
	v_mov_b64_e32 v[4:5], 0
	v_mov_b64_e32 v[6:7], 0
	v_mov_b64_e32 v[8:9], 0
	v_mov_b64_e32 v[10:11], 0
	v_mov_b64_e32 v[12:13], 0
	v_mov_b64_e32 v[14:15], 0
	v_mov_b64_e32 v[16:17], 0
	v_mov_b64_e32 v[18:19], 0
	v_mov_b64_e32 v[20:21], 0
	v_mov_b64_e32 v[22:23], 0
	v_mov_b64_e32 v[24:25], 0
	v_mov_b64_e32 v[26:27], 0
	v_mov_b64_e32 v[28:29], 0
	v_mov_b64_e32 v[30:31], 0
	v_mov_b64_e32 v[32:33], 0
	v_mov_b64_e32 v[34:35], 0
	v_mov_b64_e32 v[36:37], 0
	v_mov_b64_e32 v[38:39], 0
	v_mov_b64_e32 v[40:41], 0
	v_mov_b64_e32 v[42:43], 0
	v_mov_b64_e32 v[44:45], 0
	v_mov_b64_e32 v[46:47], 0
	v_mov_b64_e32 v[48:49], 0
	v_mov_b64_e32 v[50:51], 0
	v_mov_b64_e32 v[52:53], 0
	v_mov_b64_e32 v[54:55], 0
	v_mov_b64_e32 v[56:57], 0
	v_mov_b64_e32 v[58:59], 0
	v_mov_b64_e32 v[60:61], 0
	v_mov_b64_e32 v[62:63], 0
	v_mov_b64_e32 v[64:65], 0
	v_mov_b64_e32 v[66:67], 0
	v_mov_b64_e32 v[68:69], 0
	v_mov_b64_e32 v[70:71], 0
	v_mov_b64_e32 v[72:73], 0
	v_mov_b64_e32 v[74:75], 0
	v_mov_b64_e32 v[76:77], 0
	v_mov_b64_e32 v[78:79], 0
	v_mov_b64_e32 v[80:81], 0
	v_mov_b64_e32 v[82:83], 0
	v_mov_b64_e32 v[84:85], 0
	v_mov_b64_e32 v[86:87], 0
	v_mov_b64_e32 v[88:89], 0
	v_mov_b64_e32 v[90:91], 0
	v_mov_b64_e32 v[92:93], 0
	v_mov_b64_e32 v[94:95], 0
	v_mov_b64_e32 v[96:97], 0
	v_mov_b64_e32 v[98:99], 0
	v_mov_b64_e32 v[100:101], 0
	v_mov_b64_e32 v[102:103], 0
	v_mov_b64_e32 v[104:105], 0
	v_mov_b64_e32 v[106:107], 0
	v_mov_b64_e32 v[108:109], 0
	v_mov_b64_e32 v[110:111], 0
	v_mov_b64_e32 v[112:113], 0
	v_mov_b64_e32 v[114:115], 0
	v_mov_b64_e32 v[116:117], 0
	v_mov_b64_e32 v[118:119], 0
	v_mov_b64_e32 v[120:121], 0
	v_mov_b64_e32 v[122:123], 0
	v_mov_b64_e32 v[124:125], 0
	v_mov_b64_e32 v[126:127], 0
	v_mov_b64_e32 v[128:129], 0
	s_addc_u32 s74, s17, 0
	s_mov_b32 s75, -2
